# weight-copy routine loops again when a smaller grid leaves a wave more than five items (no change for the 256-workgroup launch)
# baseline (speedup 1.0000x reference)
.Ltr_done:
	s_waitcnt vmcnt(0)
	s_cmp_lt_u32 s2, 0x27d8
	s_cbranch_scc1 .Ltr_w0
	v_and_b32_e32 v16, 31, v153
	s_load_dwordx16 s[8:23], s[0:1], 0xc0
	s_waitcnt lgkmcnt(0)
